# scan loader waves stream the next record into LDS with global_load_lds instead of VGPR ring + ds_write
# speedup vs baseline: 1.0280x; 1.0034x over previous
.LBB0_381:
	s_and_b64 vcc, exec, s[76:77]
	v_readlane_b32 s76, v255, 33
	v_readlane_b32 s78, v255, 35
	v_readlane_b32 s80, v255, 37
	s_mov_b32 s75, s82
	v_readlane_b32 s77, v255, 34
	v_readlane_b32 s79, v255, 36
	v_readlane_b32 s81, v255, 38
	s_cbranch_vccz .LBB0_373
	v_readfirstlane_b32 s4, v212
	v_and_b32_e32 v0, 63, v212
	s_lshr_b32 s4, s4, 6
	s_sub_i32 s4, s4, 4
	s_lshl_b32 s27, s4, 14
	v_lshl_add_u32 v0, v0, 4, s27
	v_add_u32_e32 v1, 0x1000, v0
	v_add_u32_e32 v2, 0x2000, v0
	v_add_u32_e32 v3, 0x3000, v0
	s_add_u32 s30, s12, 0xf400
	s_addc_u32 s31, s13, 0
	s_movk_i32 s28, 1
.Lscan_ld_loop:
	s_and_b32 s29, s28, 1
	s_mul_i32 s29, s29, 0xf400
	s_add_i32 s29, s29, s27
	s_mov_b32 m0, s29
	s_nop 0
	global_load_lds_dwordx4 v0, s[30:31]
	global_load_lds_dwordx4 v0, s[30:31] offset:1024
	global_load_lds_dwordx4 v0, s[30:31] offset:2048
	global_load_lds_dwordx4 v0, s[30:31] offset:3072
	s_add_i32 m0, s29, 0x1000
	s_nop 0
	global_load_lds_dwordx4 v1, s[30:31]
	global_load_lds_dwordx4 v1, s[30:31] offset:1024
	global_load_lds_dwordx4 v1, s[30:31] offset:2048
	global_load_lds_dwordx4 v1, s[30:31] offset:3072
	s_add_i32 m0, s29, 0x2000
	s_nop 0
	global_load_lds_dwordx4 v2, s[30:31]
	global_load_lds_dwordx4 v2, s[30:31] offset:1024
	global_load_lds_dwordx4 v2, s[30:31] offset:2048
	global_load_lds_dwordx4 v2, s[30:31] offset:3072
	s_add_i32 m0, s29, 0x3000
	s_nop 0
	global_load_lds_dwordx4 v3, s[30:31]
	s_cmp_eq_u32 s4, 3
	s_cbranch_scc1 .Lscan_ld_skip
	global_load_lds_dwordx4 v3, s[30:31] offset:1024
	global_load_lds_dwordx4 v3, s[30:31] offset:2048
	global_load_lds_dwordx4 v3, s[30:31] offset:3072
.Lscan_ld_skip:
	s_add_u32 s30, s30, 0xf400
	s_addc_u32 s31, s31, 0
	s_add_i32 s28, s28, 1
	s_waitcnt vmcnt(0)
	s_barrier
	s_cmp_lt_u32 s28, 32
	s_cbranch_scc1 .Lscan_ld_loop
	s_barrier
	s_branch .LBB0_373
